# grid barrier: waiting blocks poll the top-level generation word directly instead of the per-XCD word (one hop less per barrier)
# baseline (speedup 1.0000x reference)
; __device__ __forceinline__ unsigned xb_ld(unsigned* p)              { return __hip_atomic_load(p, __ATOMIC_RELAXED, __HIP_MEMORY_SCOPE_AGENT); }
; __device__ __forceinline__ unsigned xb_add(unsigned* p, unsigned v) { return __hip_atomic_fetch_add(p, v, __ATOMIC_RELAXED, __HIP_MEMORY_SCOPE_AGENT); }
; #define XB_SPIN(cond, bar) do { unsigned _sp = 0; while (cond) { __builtin_amdgcn_s_sleep(1); \
;     if ((++_sp & 255u) == 0u) { if (xb_ld(&(bar)[XB_TMO])) break; if (_sp > XB_SPIN_CAP) { atomicAdd(&(bar)[XB_TMO], 1u); break; } } } } while (0)
; __device__ __forceinline__ void xcd_barrier(const XcdBarrier& b) {
;     asm volatile("s_waitcnt vmcnt(0)" ::: "memory");
;     __syncthreads();
;     if (opaque_tid() == 0) {
;         unsigned* bar = b.bar;
;         __builtin_amdgcn_s_waitcnt(0);
;         unsigned nloc = b.st[0], nx = b.st[1];
;         if (nloc == 0u) { xcd_barrier_complete(bar, b.x, nloc, nx); b.st[0] = nloc; b.st[1] = nx; }
;         const unsigned old = xb_add(&bar[XB_XSUB(b.x)], 1u);
;         const unsigned gen = old / nloc;
;         if (old + 1u == (gen + 1u) * nloc) {
;             __builtin_amdgcn_fence(__ATOMIC_RELEASE, "agent");
;             asm volatile("s_waitcnt vmcnt(0)" ::: "memory");
;             const unsigned og = xb_add(&bar[XB_TOP], 1u);
;             const unsigned tg = og / nx;
;             if (og + 1u == (tg + 1u) * nx) xb_add(&bar[XB_TOPGEN], 1u);
;             else XB_SPIN(xb_ld(&bar[XB_TOPGEN]) == tg, bar);
;             __builtin_amdgcn_fence(__ATOMIC_ACQUIRE, "agent");
;             xb_add(&bar[XB_XGEN(b.x)], 1u);
;             asm volatile("s_waitcnt vmcnt(0)" ::: "memory");
;         } else {
;             XB_SPIN(xb_ld(&bar[XB_XGEN(b.x)]) == gen, bar);
;             __builtin_amdgcn_fence(__ATOMIC_ACQUIRE, "agent");
;             asm volatile("s_waitcnt vmcnt(0)" ::: "memory");
.LBB0_221:
	s_or_b64 exec, exec, s[10:11]
	v_cvt_f32_u32_e32 v4, v2
	s_waitcnt vmcnt(0)
	v_readfirstlane_b32 s0, v3
	v_sub_u32_e32 v3, 0, v2
	v_rcp_iflag_f32_e32 v4, v4
	v_add_u32_e32 v5, s0, v1
	v_mul_f32_e32 v4, 0x4f7ffffe, v4
	v_cvt_u32_f32_e32 v4, v4
	v_mul_lo_u32 v1, v3, v4
	v_mul_hi_u32 v1, v4, v1
	v_add_u32_e32 v1, v4, v1
	v_mul_hi_u32 v1, v5, v1
	v_mul_lo_u32 v3, v1, v2
	v_sub_u32_e32 v3, v5, v3
	v_add_u32_e32 v4, 1, v1
	v_cmp_ge_u32_e32 vcc, v3, v2
	s_nop 1
	v_cndmask_b32_e32 v1, v1, v4, vcc
	v_sub_u32_e32 v4, v3, v2
	v_cndmask_b32_e32 v3, v3, v4, vcc
	v_add_u32_e32 v4, 1, v1
	v_cmp_ge_u32_e32 vcc, v3, v2
	v_add_u32_e32 v3, 1, v5
	s_nop 0
	v_cndmask_b32_e32 v1, v1, v4, vcc
	v_mul_lo_u32 v4, v2, v1
	v_add_u32_e32 v2, v4, v2
	v_cmp_ne_u32_e32 vcc, v3, v2
	s_and_saveexec_b64 s[0:1], vcc
	s_xor_b64 s[6:7], exec, s[0:1]
	s_cbranch_execz .LBB0_235
	s_waitcnt lgkmcnt(0)
	v_mov_b32_e32 v0, 0x3500
	global_load_dword v0, v0, s[74:75] sc1
	s_add_u32 s12, s74, 0x3500
	s_addc_u32 s13, s75, 0
	s_waitcnt vmcnt(0)
	v_cmp_eq_u32_e32 vcc, v0, v1
	s_and_saveexec_b64 s[10:11], vcc
	s_cbranch_execz .LBB0_234
	s_mov_b32 s0, 1
	s_mov_b64 s[52:53], 0
	v_mov_b32_e32 v0, 0
	s_branch .LBB0_225

; __device__ __forceinline__ unsigned xb_ld(unsigned* p)              { return __hip_atomic_load(p, __ATOMIC_RELAXED, __HIP_MEMORY_SCOPE_AGENT); }
; __device__ __forceinline__ unsigned xb_add(unsigned* p, unsigned v) { return __hip_atomic_fetch_add(p, v, __ATOMIC_RELAXED, __HIP_MEMORY_SCOPE_AGENT); }
; #define XB_SPIN(cond, bar) do { unsigned _sp = 0; while (cond) { __builtin_amdgcn_s_sleep(1); \
;     if ((++_sp & 255u) == 0u) { if (xb_ld(&(bar)[XB_TMO])) break; if (_sp > XB_SPIN_CAP) { atomicAdd(&(bar)[XB_TMO], 1u); break; } } } } while (0)
; __device__ __forceinline__ void xcd_barrier(const XcdBarrier& b) {
;     ...
;             else XB_SPIN(xb_ld(&bar[XB_TOPGEN]) == tg, bar);
;             __builtin_amdgcn_fence(__ATOMIC_ACQUIRE, "agent");
;             xb_add(&bar[XB_XGEN(b.x)], 1u);
;             asm volatile("s_waitcnt vmcnt(0)" ::: "memory");
;         } else {
;             XB_SPIN(xb_ld(&bar[XB_XGEN(b.x)]) == gen, bar);
;             __builtin_amdgcn_fence(__ATOMIC_ACQUIRE, "agent");
;             asm volatile("s_waitcnt vmcnt(0)" ::: "memory");
.Lb2wait_l0:
	s_nop 0
	s_nop 0
	s_nop 0
	s_nop 0
	s_nop 0
	s_nop 0
	s_nop 0
	s_nop 0
	s_nop 0
	s_nop 0
	s_nop 0
	s_nop 0
	v_mov_b32_e32 v0, 0x3500
	global_load_dword v0, v0, s[74:75] sc1
	s_add_u32 s52, s74, 0x3500
	s_addc_u32 s53, s75, 0
	s_waitcnt vmcnt(0)
	v_cmp_eq_u32_e32 vcc, v0, v1
	s_and_saveexec_b64 s[10:11], vcc
	s_cbranch_execz .LBB0_538
	s_mov_b32 s0, 1
	s_mov_b64 s[62:63], 0
	v_mov_b32_e32 v0, 0
	s_branch .LBB0_529

; __device__ __forceinline__ unsigned xb_ld(unsigned* p)              { return __hip_atomic_load(p, __ATOMIC_RELAXED, __HIP_MEMORY_SCOPE_AGENT); }
; __device__ __forceinline__ unsigned xb_add(unsigned* p, unsigned v) { return __hip_atomic_fetch_add(p, v, __ATOMIC_RELAXED, __HIP_MEMORY_SCOPE_AGENT); }
; #define XB_SPIN(cond, bar) do { unsigned _sp = 0; while (cond) { __builtin_amdgcn_s_sleep(1); \
;     if ((++_sp & 255u) == 0u) { if (xb_ld(&(bar)[XB_TMO])) break; if (_sp > XB_SPIN_CAP) { atomicAdd(&(bar)[XB_TMO], 1u); break; } } } } while (0)
; __device__ __forceinline__ void xcd_barrier(const XcdBarrier& b) {
;     ...
;         const unsigned old = xb_add(&bar[XB_XSUB(b.x)], 1u);
;         const unsigned gen = old / nloc;
;         if (old + 1u == (gen + 1u) * nloc) {
;             __builtin_amdgcn_fence(__ATOMIC_RELEASE, "agent");
;             asm volatile("s_waitcnt vmcnt(0)" ::: "memory");
;             const unsigned og = xb_add(&bar[XB_TOP], 1u);
;             const unsigned tg = og / nx;
;             if (og + 1u == (tg + 1u) * nx) xb_add(&bar[XB_TOPGEN], 1u);
;             else XB_SPIN(xb_ld(&bar[XB_TOPGEN]) == tg, bar);
;             __builtin_amdgcn_fence(__ATOMIC_ACQUIRE, "agent");
;             xb_add(&bar[XB_XGEN(b.x)], 1u);
;             asm volatile("s_waitcnt vmcnt(0)" ::: "memory");
;         } else {
;             XB_SPIN(xb_ld(&bar[XB_XGEN(b.x)]) == gen, bar);
;             __builtin_amdgcn_fence(__ATOMIC_ACQUIRE, "agent");
;             asm volatile("s_waitcnt vmcnt(0)" ::: "memory");
.LBB0_781:
	s_or_b64 exec, exec, s[8:9]
	v_cvt_f32_u32_e32 v4, v2
	s_waitcnt vmcnt(0)
	v_readfirstlane_b32 s0, v3
	v_sub_u32_e32 v3, 0, v2
	v_rcp_iflag_f32_e32 v4, v4
	v_add_u32_e32 v5, s0, v1
	v_mul_f32_e32 v4, 0x4f7ffffe, v4
	v_cvt_u32_f32_e32 v4, v4
	v_mul_lo_u32 v1, v3, v4
	v_mul_hi_u32 v1, v4, v1
	v_add_u32_e32 v1, v4, v1
	v_mul_hi_u32 v1, v5, v1
	v_mul_lo_u32 v3, v1, v2
	v_sub_u32_e32 v3, v5, v3
	v_add_u32_e32 v4, 1, v1
	v_cmp_ge_u32_e32 vcc, v3, v2
	s_nop 1
	v_cndmask_b32_e32 v1, v1, v4, vcc
	v_sub_u32_e32 v4, v3, v2
	v_cndmask_b32_e32 v3, v3, v4, vcc
	v_add_u32_e32 v4, 1, v1
	v_cmp_ge_u32_e32 vcc, v3, v2
	v_add_u32_e32 v3, 1, v5
	s_nop 0
	v_cndmask_b32_e32 v1, v1, v4, vcc
	v_mul_lo_u32 v4, v2, v1
	v_add_u32_e32 v2, v4, v2
	v_cmp_ne_u32_e32 vcc, v3, v2
	s_and_saveexec_b64 s[0:1], vcc
	s_xor_b64 s[6:7], exec, s[0:1]
	s_cbranch_execz .LBB0_795
	s_waitcnt lgkmcnt(0)
	v_mov_b32_e32 v0, 0x3500
	global_load_dword v0, v0, s[74:75] sc1
	s_add_u32 s10, s74, 0x3500
	s_addc_u32 s11, s75, 0
	s_waitcnt vmcnt(0)
	v_cmp_eq_u32_e32 vcc, v0, v1
	s_and_saveexec_b64 s[8:9], vcc
	s_cbranch_execz .LBB0_794
	s_mov_b32 s0, 1
	s_mov_b64 s[62:63], 0
	v_mov_b32_e32 v0, 0
	s_branch .LBB0_785

; __device__ __forceinline__ unsigned xb_ld(unsigned* p)              { return __hip_atomic_load(p, __ATOMIC_RELAXED, __HIP_MEMORY_SCOPE_AGENT); }
; __device__ __forceinline__ unsigned xb_add(unsigned* p, unsigned v) { return __hip_atomic_fetch_add(p, v, __ATOMIC_RELAXED, __HIP_MEMORY_SCOPE_AGENT); }
; #define XB_SPIN(cond, bar) do { unsigned _sp = 0; while (cond) { __builtin_amdgcn_s_sleep(1); \
;     if ((++_sp & 255u) == 0u) { if (xb_ld(&(bar)[XB_TMO])) break; if (_sp > XB_SPIN_CAP) { atomicAdd(&(bar)[XB_TMO], 1u); break; } } } } while (0)
; __device__ __forceinline__ void xcd_barrier(const XcdBarrier& b) {
;     ...
;         const unsigned old = xb_add(&bar[XB_XSUB(b.x)], 1u);
;         const unsigned gen = old / nloc;
;         if (old + 1u == (gen + 1u) * nloc) {
;             __builtin_amdgcn_fence(__ATOMIC_RELEASE, "agent");
;             asm volatile("s_waitcnt vmcnt(0)" ::: "memory");
;             const unsigned og = xb_add(&bar[XB_TOP], 1u);
;             const unsigned tg = og / nx;
;             if (og + 1u == (tg + 1u) * nx) xb_add(&bar[XB_TOPGEN], 1u);
;             else XB_SPIN(xb_ld(&bar[XB_TOPGEN]) == tg, bar);
;             __builtin_amdgcn_fence(__ATOMIC_ACQUIRE, "agent");
;             xb_add(&bar[XB_XGEN(b.x)], 1u);
;             asm volatile("s_waitcnt vmcnt(0)" ::: "memory");
;         } else {
;             XB_SPIN(xb_ld(&bar[XB_XGEN(b.x)]) == gen, bar);
;             __builtin_amdgcn_fence(__ATOMIC_ACQUIRE, "agent");
;             asm volatile("s_waitcnt vmcnt(0)" ::: "memory");
.LBB0_1416:
	s_or_b64 exec, exec, s[10:11]
	v_cvt_f32_u32_e32 v4, v2
	s_waitcnt vmcnt(0)
	v_readfirstlane_b32 s0, v3
	v_sub_u32_e32 v3, 0, v2
	v_rcp_iflag_f32_e32 v4, v4
	v_add_u32_e32 v5, s0, v1
	v_mul_f32_e32 v4, 0x4f7ffffe, v4
	v_cvt_u32_f32_e32 v4, v4
	v_mul_lo_u32 v1, v3, v4
	v_mul_hi_u32 v1, v4, v1
	v_add_u32_e32 v1, v4, v1
	v_mul_hi_u32 v1, v5, v1
	v_mul_lo_u32 v3, v1, v2
	v_sub_u32_e32 v3, v5, v3
	v_add_u32_e32 v4, 1, v1
	v_cmp_ge_u32_e32 vcc, v3, v2
	s_nop 1
	v_cndmask_b32_e32 v1, v1, v4, vcc
	v_sub_u32_e32 v4, v3, v2
	v_cndmask_b32_e32 v3, v3, v4, vcc
	v_add_u32_e32 v4, 1, v1
	v_cmp_ge_u32_e32 vcc, v3, v2
	v_add_u32_e32 v3, 1, v5
	s_nop 0
	v_cndmask_b32_e32 v1, v1, v4, vcc
	v_mul_lo_u32 v4, v2, v1
	v_add_u32_e32 v2, v4, v2
	v_cmp_ne_u32_e32 vcc, v3, v2
	s_and_saveexec_b64 s[0:1], vcc
	s_xor_b64 s[8:9], exec, s[0:1]
	s_cbranch_execz .LBB0_1430
	s_waitcnt lgkmcnt(0)
	s_cmp_lt_i32 s92, 64
	s_cbranch_scc1 .LBB0_1430
	s_nop 0
	s_nop 0
	s_nop 0
	s_nop 0
	s_nop 0
	s_nop 0
	s_nop 0
	s_nop 0
	s_nop 0
	s_nop 0
	s_nop 0
	s_nop 0
	s_nop 0
	s_nop 0
	v_mov_b32_e32 v0, 0x3500
	global_load_dword v0, v0, s[74:75] sc1
	s_add_u32 s62, s74, 0x3500
	s_addc_u32 s63, s75, 0
	s_waitcnt vmcnt(0)
	v_cmp_eq_u32_e32 vcc, v0, v1
	s_and_saveexec_b64 s[10:11], vcc
	s_cbranch_execz .LBB0_1429
	s_mov_b32 s0, 1
	s_mov_b64 s[66:67], 0
	v_mov_b32_e32 v0, 0
	s_branch .LBB0_1420

; __device__ __forceinline__ unsigned xb_ld(unsigned* p)              { return __hip_atomic_load(p, __ATOMIC_RELAXED, __HIP_MEMORY_SCOPE_AGENT); }
; __device__ __forceinline__ unsigned xb_add(unsigned* p, unsigned v) { return __hip_atomic_fetch_add(p, v, __ATOMIC_RELAXED, __HIP_MEMORY_SCOPE_AGENT); }
; #define XB_SPIN(cond, bar) do { unsigned _sp = 0; while (cond) { __builtin_amdgcn_s_sleep(1); \
;     if ((++_sp & 255u) == 0u) { if (xb_ld(&(bar)[XB_TMO])) break; if (_sp > XB_SPIN_CAP) { atomicAdd(&(bar)[XB_TMO], 1u); break; } } } } while (0)
; __device__ __forceinline__ void xcd_barrier(const XcdBarrier& b) {
;     ...
;         const unsigned old = xb_add(&bar[XB_XSUB(b.x)], 1u);
;         const unsigned gen = old / nloc;
;         if (old + 1u == (gen + 1u) * nloc) {
;             __builtin_amdgcn_fence(__ATOMIC_RELEASE, "agent");
;             asm volatile("s_waitcnt vmcnt(0)" ::: "memory");
;             const unsigned og = xb_add(&bar[XB_TOP], 1u);
;             const unsigned tg = og / nx;
;             if (og + 1u == (tg + 1u) * nx) xb_add(&bar[XB_TOPGEN], 1u);
;             else XB_SPIN(xb_ld(&bar[XB_TOPGEN]) == tg, bar);
;             __builtin_amdgcn_fence(__ATOMIC_ACQUIRE, "agent");
;             xb_add(&bar[XB_XGEN(b.x)], 1u);
;             asm volatile("s_waitcnt vmcnt(0)" ::: "memory");
;         } else {
;             XB_SPIN(xb_ld(&bar[XB_XGEN(b.x)]) == gen, bar);
;             __builtin_amdgcn_fence(__ATOMIC_ACQUIRE, "agent");
;             asm volatile("s_waitcnt vmcnt(0)" ::: "memory");
.LBB0_2210:
	s_or_b64 exec, exec, s[54:55]
	v_cvt_f32_u32_e32 v4, v2
	s_waitcnt vmcnt(0)
	v_readfirstlane_b32 s0, v3
	v_sub_u32_e32 v3, 0, v2
	v_rcp_iflag_f32_e32 v4, v4
	v_add_u32_e32 v5, s0, v1
	v_mul_f32_e32 v4, 0x4f7ffffe, v4
	v_cvt_u32_f32_e32 v4, v4
	v_mul_lo_u32 v1, v3, v4
	v_mul_hi_u32 v1, v4, v1
	v_add_u32_e32 v1, v4, v1
	v_mul_hi_u32 v1, v5, v1
	v_mul_lo_u32 v3, v1, v2
	v_sub_u32_e32 v3, v5, v3
	v_add_u32_e32 v4, 1, v1
	v_cmp_ge_u32_e32 vcc, v3, v2
	s_nop 1
	v_cndmask_b32_e32 v1, v1, v4, vcc
	v_sub_u32_e32 v4, v3, v2
	v_cndmask_b32_e32 v3, v3, v4, vcc
	v_add_u32_e32 v4, 1, v1
	v_cmp_ge_u32_e32 vcc, v3, v2
	v_add_u32_e32 v3, 1, v5
	s_nop 0
	v_cndmask_b32_e32 v1, v1, v4, vcc
	v_mul_lo_u32 v4, v2, v1
	v_add_u32_e32 v2, v4, v2
	v_cmp_ne_u32_e32 vcc, v3, v2
	s_and_saveexec_b64 s[0:1], vcc
	s_xor_b64 s[10:11], exec, s[0:1]
	s_cbranch_execz .LBB0_2224
	s_waitcnt lgkmcnt(0)
	v_mov_b32_e32 v0, 0x3500
	global_load_dword v0, v0, s[74:75] sc1
	s_add_u32 s62, s74, 0x3500
	s_addc_u32 s63, s75, 0
	s_waitcnt vmcnt(0)
	v_cmp_eq_u32_e32 vcc, v0, v1
	s_and_saveexec_b64 s[54:55], vcc
	s_cbranch_execz .LBB0_2223
	s_mov_b32 s0, 1
	s_mov_b64 s[66:67], 0
	v_mov_b32_e32 v0, 0
	s_branch .LBB0_2214

; __device__ __forceinline__ unsigned xb_ld(unsigned* p)              { return __hip_atomic_load(p, __ATOMIC_RELAXED, __HIP_MEMORY_SCOPE_AGENT); }
; __device__ __forceinline__ unsigned xb_add(unsigned* p, unsigned v) { return __hip_atomic_fetch_add(p, v, __ATOMIC_RELAXED, __HIP_MEMORY_SCOPE_AGENT); }
; #define XB_SPIN(cond, bar) do { unsigned _sp = 0; while (cond) { __builtin_amdgcn_s_sleep(1); \
;     if ((++_sp & 255u) == 0u) { if (xb_ld(&(bar)[XB_TMO])) break; if (_sp > XB_SPIN_CAP) { atomicAdd(&(bar)[XB_TMO], 1u); break; } } } } while (0)
; __device__ __forceinline__ void xcd_barrier(const XcdBarrier& b) {
;     ...
;         const unsigned old = xb_add(&bar[XB_XSUB(b.x)], 1u);
;         const unsigned gen = old / nloc;
;         if (old + 1u == (gen + 1u) * nloc) {
;             __builtin_amdgcn_fence(__ATOMIC_RELEASE, "agent");
;             asm volatile("s_waitcnt vmcnt(0)" ::: "memory");
;             const unsigned og = xb_add(&bar[XB_TOP], 1u);
;             const unsigned tg = og / nx;
;             if (og + 1u == (tg + 1u) * nx) xb_add(&bar[XB_TOPGEN], 1u);
;             else XB_SPIN(xb_ld(&bar[XB_TOPGEN]) == tg, bar);
;             __builtin_amdgcn_fence(__ATOMIC_ACQUIRE, "agent");
;             xb_add(&bar[XB_XGEN(b.x)], 1u);
;             asm volatile("s_waitcnt vmcnt(0)" ::: "memory");
;         } else {
;             XB_SPIN(xb_ld(&bar[XB_XGEN(b.x)]) == gen, bar);
;             __builtin_amdgcn_fence(__ATOMIC_ACQUIRE, "agent");
;             asm volatile("s_waitcnt vmcnt(0)" ::: "memory");
.LBB0_2281:
	s_or_b64 exec, exec, s[16:17]
	v_cvt_f32_u32_e32 v4, v2
	s_waitcnt vmcnt(0)
	v_readfirstlane_b32 s0, v3
	v_sub_u32_e32 v3, 0, v2
	v_rcp_iflag_f32_e32 v4, v4
	v_add_u32_e32 v5, s0, v1
	v_mul_f32_e32 v4, 0x4f7ffffe, v4
	v_cvt_u32_f32_e32 v4, v4
	v_mul_lo_u32 v1, v3, v4
	v_mul_hi_u32 v1, v4, v1
	v_add_u32_e32 v1, v4, v1
	v_mul_hi_u32 v1, v5, v1
	v_mul_lo_u32 v3, v1, v2
	v_sub_u32_e32 v3, v5, v3
	v_add_u32_e32 v4, 1, v1
	v_cmp_ge_u32_e32 vcc, v3, v2
	s_nop 1
	v_cndmask_b32_e32 v1, v1, v4, vcc
	v_sub_u32_e32 v4, v3, v2
	v_cndmask_b32_e32 v3, v3, v4, vcc
	v_add_u32_e32 v4, 1, v1
	v_cmp_ge_u32_e32 vcc, v3, v2
	v_add_u32_e32 v3, 1, v5
	s_nop 0
	v_cndmask_b32_e32 v1, v1, v4, vcc
	v_mul_lo_u32 v4, v2, v1
	v_add_u32_e32 v2, v4, v2
	v_cmp_ne_u32_e32 vcc, v3, v2
	s_and_saveexec_b64 s[0:1], vcc
	s_xor_b64 s[10:11], exec, s[0:1]
	s_cbranch_execz .LBB0_2295
	s_waitcnt lgkmcnt(0)
	v_mov_b32_e32 v0, 0x3500
	global_load_dword v0, v0, s[74:75] sc1
	s_add_u32 s18, s74, 0x3500
	s_addc_u32 s19, s75, 0
	s_waitcnt vmcnt(0)
	v_cmp_eq_u32_e32 vcc, v0, v1
	s_and_saveexec_b64 s[16:17], vcc
	s_cbranch_execz .LBB0_2294
	s_mov_b32 s0, 1
	s_mov_b64 s[54:55], 0
	v_mov_b32_e32 v0, 0
	s_branch .LBB0_2285

; __device__ __forceinline__ unsigned xb_ld(unsigned* p)              { return __hip_atomic_load(p, __ATOMIC_RELAXED, __HIP_MEMORY_SCOPE_AGENT); }
; __device__ __forceinline__ unsigned xb_add(unsigned* p, unsigned v) { return __hip_atomic_fetch_add(p, v, __ATOMIC_RELAXED, __HIP_MEMORY_SCOPE_AGENT); }
; #define XB_SPIN(cond, bar) do { unsigned _sp = 0; while (cond) { __builtin_amdgcn_s_sleep(1); \
;     if ((++_sp & 255u) == 0u) { if (xb_ld(&(bar)[XB_TMO])) break; if (_sp > XB_SPIN_CAP) { atomicAdd(&(bar)[XB_TMO], 1u); break; } } } } while (0)
; __device__ __forceinline__ void xcd_barrier(const XcdBarrier& b) {
;     ...
;         const unsigned old = xb_add(&bar[XB_XSUB(b.x)], 1u);
;         const unsigned gen = old / nloc;
;         if (old + 1u == (gen + 1u) * nloc) {
;             __builtin_amdgcn_fence(__ATOMIC_RELEASE, "agent");
;             asm volatile("s_waitcnt vmcnt(0)" ::: "memory");
;             const unsigned og = xb_add(&bar[XB_TOP], 1u);
;             const unsigned tg = og / nx;
;             if (og + 1u == (tg + 1u) * nx) xb_add(&bar[XB_TOPGEN], 1u);
;             else XB_SPIN(xb_ld(&bar[XB_TOPGEN]) == tg, bar);
;             __builtin_amdgcn_fence(__ATOMIC_ACQUIRE, "agent");
;             xb_add(&bar[XB_XGEN(b.x)], 1u);
;             asm volatile("s_waitcnt vmcnt(0)" ::: "memory");
;         } else {
;             XB_SPIN(xb_ld(&bar[XB_XGEN(b.x)]) == gen, bar);
;             __builtin_amdgcn_fence(__ATOMIC_ACQUIRE, "agent");
;             asm volatile("s_waitcnt vmcnt(0)" ::: "memory");
.LBB0_2358:
	s_or_b64 exec, exec, s[18:19]
	v_cvt_f32_u32_e32 v4, v2
	s_waitcnt vmcnt(0)
	v_readfirstlane_b32 s0, v3
	v_sub_u32_e32 v3, 0, v2
	v_rcp_iflag_f32_e32 v4, v4
	v_add_u32_e32 v5, s0, v1
	v_mul_f32_e32 v4, 0x4f7ffffe, v4
	v_cvt_u32_f32_e32 v4, v4
	v_mul_lo_u32 v1, v3, v4
	v_mul_hi_u32 v1, v4, v1
	v_add_u32_e32 v1, v4, v1
	v_mul_hi_u32 v1, v5, v1
	v_mul_lo_u32 v3, v1, v2
	v_sub_u32_e32 v3, v5, v3
	v_add_u32_e32 v4, 1, v1
	v_cmp_ge_u32_e32 vcc, v3, v2
	s_nop 1
	v_cndmask_b32_e32 v1, v1, v4, vcc
	v_sub_u32_e32 v4, v3, v2
	v_cndmask_b32_e32 v3, v3, v4, vcc
	v_add_u32_e32 v4, 1, v1
	v_cmp_ge_u32_e32 vcc, v3, v2
	v_add_u32_e32 v3, 1, v5
	s_nop 0
	v_cndmask_b32_e32 v1, v1, v4, vcc
	v_mul_lo_u32 v4, v2, v1
	v_add_u32_e32 v2, v4, v2
	v_cmp_ne_u32_e32 vcc, v3, v2
	s_and_saveexec_b64 s[0:1], vcc
	s_xor_b64 s[10:11], exec, s[0:1]
	s_cbranch_execz .LBB0_2372
	s_waitcnt lgkmcnt(0)
	v_mov_b32_e32 v0, 0x3500
	global_load_dword v0, v0, s[74:75] sc1
	s_add_u32 s30, s74, 0x3500
	s_addc_u32 s31, s75, 0
	s_waitcnt vmcnt(0)
	v_cmp_eq_u32_e32 vcc, v0, v1
	s_and_saveexec_b64 s[18:19], vcc
	s_cbranch_execz .LBB0_2371
	s_mov_b32 s0, 1
	s_mov_b64 s[54:55], 0
	v_mov_b32_e32 v0, 0
	s_branch .LBB0_2362

; __device__ __forceinline__ unsigned xb_ld(unsigned* p)              { return __hip_atomic_load(p, __ATOMIC_RELAXED, __HIP_MEMORY_SCOPE_AGENT); }
; __device__ __forceinline__ unsigned xb_add(unsigned* p, unsigned v) { return __hip_atomic_fetch_add(p, v, __ATOMIC_RELAXED, __HIP_MEMORY_SCOPE_AGENT); }
; #define XB_SPIN(cond, bar) do { unsigned _sp = 0; while (cond) { __builtin_amdgcn_s_sleep(1); \
;     if ((++_sp & 255u) == 0u) { if (xb_ld(&(bar)[XB_TMO])) break; if (_sp > XB_SPIN_CAP) { atomicAdd(&(bar)[XB_TMO], 1u); break; } } } } while (0)
; __device__ __forceinline__ void xcd_barrier(const XcdBarrier& b) {
;     ...
;         const unsigned old = xb_add(&bar[XB_XSUB(b.x)], 1u);
;         const unsigned gen = old / nloc;
;         if (old + 1u == (gen + 1u) * nloc) {
;             __builtin_amdgcn_fence(__ATOMIC_RELEASE, "agent");
;             asm volatile("s_waitcnt vmcnt(0)" ::: "memory");
;             const unsigned og = xb_add(&bar[XB_TOP], 1u);
;             const unsigned tg = og / nx;
;             if (og + 1u == (tg + 1u) * nx) xb_add(&bar[XB_TOPGEN], 1u);
;             else XB_SPIN(xb_ld(&bar[XB_TOPGEN]) == tg, bar);
;             __builtin_amdgcn_fence(__ATOMIC_ACQUIRE, "agent");
;             xb_add(&bar[XB_XGEN(b.x)], 1u);
;             asm volatile("s_waitcnt vmcnt(0)" ::: "memory");
;         } else {
;             XB_SPIN(xb_ld(&bar[XB_XGEN(b.x)]) == gen, bar);
;             __builtin_amdgcn_fence(__ATOMIC_ACQUIRE, "agent");
;             asm volatile("s_waitcnt vmcnt(0)" ::: "memory");
.LBB0_2532:
	s_or_b64 exec, exec, s[10:11]
	v_cvt_f32_u32_e32 v4, v2
	s_waitcnt vmcnt(0)
	v_readfirstlane_b32 s2, v3
	v_sub_u32_e32 v3, 0, v2
	v_rcp_iflag_f32_e32 v4, v4
	v_add_u32_e32 v5, s2, v1
	v_mul_f32_e32 v4, 0x4f7ffffe, v4
	v_cvt_u32_f32_e32 v4, v4
	v_mul_lo_u32 v1, v3, v4
	v_mul_hi_u32 v1, v4, v1
	v_add_u32_e32 v1, v4, v1
	v_mul_hi_u32 v1, v5, v1
	v_mul_lo_u32 v3, v1, v2
	v_sub_u32_e32 v3, v5, v3
	v_add_u32_e32 v4, 1, v1
	v_cmp_ge_u32_e32 vcc, v3, v2
	s_nop 1
	v_cndmask_b32_e32 v1, v1, v4, vcc
	v_sub_u32_e32 v4, v3, v2
	v_cndmask_b32_e32 v3, v3, v4, vcc
	v_add_u32_e32 v4, 1, v1
	v_cmp_ge_u32_e32 vcc, v3, v2
	v_add_u32_e32 v3, 1, v5
	s_nop 0
	v_cndmask_b32_e32 v1, v1, v4, vcc
	v_mul_lo_u32 v4, v2, v1
	v_add_u32_e32 v2, v4, v2
	v_cmp_ne_u32_e32 vcc, v3, v2
	s_and_saveexec_b64 s[2:3], vcc
	s_xor_b64 s[8:9], exec, s[2:3]
	s_cbranch_execz .LBB0_2546
	s_waitcnt lgkmcnt(0)
	v_mov_b32_e32 v0, 0x3500
	global_load_dword v0, v0, s[74:75] sc1
	s_add_u32 s30, s74, 0x3500
	s_addc_u32 s31, s75, 0
	s_waitcnt vmcnt(0)
	v_cmp_eq_u32_e32 vcc, v0, v1
	s_and_saveexec_b64 s[10:11], vcc
	s_cbranch_execz .LBB0_2545
	s_mov_b32 s2, 1
	s_mov_b64 s[54:55], 0
	v_mov_b32_e32 v0, 0
	s_branch .LBB0_2536

; __device__ __forceinline__ unsigned xb_ld(unsigned* p)              { return __hip_atomic_load(p, __ATOMIC_RELAXED, __HIP_MEMORY_SCOPE_AGENT); }
; __device__ __forceinline__ unsigned xb_add(unsigned* p, unsigned v) { return __hip_atomic_fetch_add(p, v, __ATOMIC_RELAXED, __HIP_MEMORY_SCOPE_AGENT); }
; #define XB_SPIN(cond, bar) do { unsigned _sp = 0; while (cond) { __builtin_amdgcn_s_sleep(1); \
;     if ((++_sp & 255u) == 0u) { if (xb_ld(&(bar)[XB_TMO])) break; if (_sp > XB_SPIN_CAP) { atomicAdd(&(bar)[XB_TMO], 1u); break; } } } } while (0)
; __device__ __forceinline__ void xcd_barrier(const XcdBarrier& b) {
;     ...
;             else XB_SPIN(xb_ld(&bar[XB_TOPGEN]) == tg, bar);
;             __builtin_amdgcn_fence(__ATOMIC_ACQUIRE, "agent");
;             xb_add(&bar[XB_XGEN(b.x)], 1u);
;             asm volatile("s_waitcnt vmcnt(0)" ::: "memory");
;         } else {
;             XB_SPIN(xb_ld(&bar[XB_XGEN(b.x)]) == gen, bar);
;             __builtin_amdgcn_fence(__ATOMIC_ACQUIRE, "agent");
;             asm volatile("s_waitcnt vmcnt(0)" ::: "memory");
.Lb2wait_l1:
	s_nop 0
	s_nop 0
	s_nop 0
	s_nop 0
	s_nop 0
	s_nop 0
	s_nop 0
	s_nop 0
	s_nop 0
	s_nop 0
	s_nop 0
	s_nop 0
	v_mov_b32_e32 v0, 0x3500
	global_load_dword v0, v0, s[74:75] sc1
	s_add_u32 s12, s74, 0x3500
	s_addc_u32 s13, s75, 0
	s_waitcnt vmcnt(0)
	v_cmp_eq_u32_e32 vcc, v0, v1
	s_and_saveexec_b64 s[10:11], vcc
	s_cbranch_execz .LBB0_2849
	s_mov_b32 s2, 1
	s_mov_b64 s[30:31], 0
	v_mov_b32_e32 v0, 0
	s_branch .LBB0_2840

; __device__ __forceinline__ unsigned xb_ld(unsigned* p)              { return __hip_atomic_load(p, __ATOMIC_RELAXED, __HIP_MEMORY_SCOPE_AGENT); }
; __device__ __forceinline__ unsigned xb_add(unsigned* p, unsigned v) { return __hip_atomic_fetch_add(p, v, __ATOMIC_RELAXED, __HIP_MEMORY_SCOPE_AGENT); }
; #define XB_SPIN(cond, bar) do { unsigned _sp = 0; while (cond) { __builtin_amdgcn_s_sleep(1); \
;     if ((++_sp & 255u) == 0u) { if (xb_ld(&(bar)[XB_TMO])) break; if (_sp > XB_SPIN_CAP) { atomicAdd(&(bar)[XB_TMO], 1u); break; } } } } while (0)
; __device__ __forceinline__ void xcd_barrier(const XcdBarrier& b) {
;     ...
;         const unsigned old = xb_add(&bar[XB_XSUB(b.x)], 1u);
;         const unsigned gen = old / nloc;
;         if (old + 1u == (gen + 1u) * nloc) {
;             __builtin_amdgcn_fence(__ATOMIC_RELEASE, "agent");
;             asm volatile("s_waitcnt vmcnt(0)" ::: "memory");
;             const unsigned og = xb_add(&bar[XB_TOP], 1u);
;             const unsigned tg = og / nx;
;             if (og + 1u == (tg + 1u) * nx) xb_add(&bar[XB_TOPGEN], 1u);
;             else XB_SPIN(xb_ld(&bar[XB_TOPGEN]) == tg, bar);
;             __builtin_amdgcn_fence(__ATOMIC_ACQUIRE, "agent");
;             xb_add(&bar[XB_XGEN(b.x)], 1u);
;             asm volatile("s_waitcnt vmcnt(0)" ::: "memory");
;         } else {
;             XB_SPIN(xb_ld(&bar[XB_XGEN(b.x)]) == gen, bar);
;             __builtin_amdgcn_fence(__ATOMIC_ACQUIRE, "agent");
;             asm volatile("s_waitcnt vmcnt(0)" ::: "memory");
.LBB0_3092:
	s_or_b64 exec, exec, s[10:11]
	v_cvt_f32_u32_e32 v4, v2
	s_waitcnt vmcnt(0)
	v_readfirstlane_b32 s2, v3
	v_sub_u32_e32 v3, 0, v2
	v_rcp_iflag_f32_e32 v4, v4
	v_add_u32_e32 v5, s2, v1
	v_mul_f32_e32 v4, 0x4f7ffffe, v4
	v_cvt_u32_f32_e32 v4, v4
	v_mul_lo_u32 v1, v3, v4
	v_mul_hi_u32 v1, v4, v1
	v_add_u32_e32 v1, v4, v1
	v_mul_hi_u32 v1, v5, v1
	v_mul_lo_u32 v3, v1, v2
	v_sub_u32_e32 v3, v5, v3
	v_add_u32_e32 v4, 1, v1
	v_cmp_ge_u32_e32 vcc, v3, v2
	s_nop 1
	v_cndmask_b32_e32 v1, v1, v4, vcc
	v_sub_u32_e32 v4, v3, v2
	v_cndmask_b32_e32 v3, v3, v4, vcc
	v_add_u32_e32 v4, 1, v1
	v_cmp_ge_u32_e32 vcc, v3, v2
	v_add_u32_e32 v3, 1, v5
	s_nop 0
	v_cndmask_b32_e32 v1, v1, v4, vcc
	v_mul_lo_u32 v4, v2, v1
	v_add_u32_e32 v2, v4, v2
	v_cmp_ne_u32_e32 vcc, v3, v2
	s_and_saveexec_b64 s[2:3], vcc
	s_xor_b64 s[8:9], exec, s[2:3]
	s_cbranch_execz .LBB0_3106
	s_waitcnt lgkmcnt(0)
	v_mov_b32_e32 v0, 0x3500
	global_load_dword v0, v0, s[74:75] sc1
	s_add_u32 s12, s74, 0x3500
	s_addc_u32 s13, s75, 0
	s_waitcnt vmcnt(0)
	v_cmp_eq_u32_e32 vcc, v0, v1
	s_and_saveexec_b64 s[10:11], vcc
	s_cbranch_execz .LBB0_3105
	s_mov_b32 s2, 1
	s_mov_b64 s[30:31], 0
	v_mov_b32_e32 v0, 0
	s_branch .LBB0_3096

; __device__ __forceinline__ unsigned xb_ld(unsigned* p)              { return __hip_atomic_load(p, __ATOMIC_RELAXED, __HIP_MEMORY_SCOPE_AGENT); }
; __device__ __forceinline__ unsigned xb_add(unsigned* p, unsigned v) { return __hip_atomic_fetch_add(p, v, __ATOMIC_RELAXED, __HIP_MEMORY_SCOPE_AGENT); }
; #define XB_SPIN(cond, bar) do { unsigned _sp = 0; while (cond) { __builtin_amdgcn_s_sleep(1); \
;     if ((++_sp & 255u) == 0u) { if (xb_ld(&(bar)[XB_TMO])) break; if (_sp > XB_SPIN_CAP) { atomicAdd(&(bar)[XB_TMO], 1u); break; } } } } while (0)
; __device__ __forceinline__ void xcd_barrier(const XcdBarrier& b) {
;     ...
;         const unsigned old = xb_add(&bar[XB_XSUB(b.x)], 1u);
;         const unsigned gen = old / nloc;
;         if (old + 1u == (gen + 1u) * nloc) {
;             __builtin_amdgcn_fence(__ATOMIC_RELEASE, "agent");
;             asm volatile("s_waitcnt vmcnt(0)" ::: "memory");
;             const unsigned og = xb_add(&bar[XB_TOP], 1u);
;             const unsigned tg = og / nx;
;             if (og + 1u == (tg + 1u) * nx) xb_add(&bar[XB_TOPGEN], 1u);
;             else XB_SPIN(xb_ld(&bar[XB_TOPGEN]) == tg, bar);
;             __builtin_amdgcn_fence(__ATOMIC_ACQUIRE, "agent");
;             xb_add(&bar[XB_XGEN(b.x)], 1u);
;             asm volatile("s_waitcnt vmcnt(0)" ::: "memory");
;         } else {
;             XB_SPIN(xb_ld(&bar[XB_XGEN(b.x)]) == gen, bar);
;             __builtin_amdgcn_fence(__ATOMIC_ACQUIRE, "agent");
;             asm volatile("s_waitcnt vmcnt(0)" ::: "memory");
.LBB0_3727:
	s_or_b64 exec, exec, s[12:13]
	v_cvt_f32_u32_e32 v4, v2
	s_waitcnt vmcnt(0)
	v_readfirstlane_b32 s2, v3
	v_sub_u32_e32 v3, 0, v2
	v_rcp_iflag_f32_e32 v4, v4
	v_add_u32_e32 v5, s2, v1
	v_mul_f32_e32 v4, 0x4f7ffffe, v4
	v_cvt_u32_f32_e32 v4, v4
	v_mul_lo_u32 v1, v3, v4
	v_mul_hi_u32 v1, v4, v1
	v_add_u32_e32 v1, v4, v1
	v_mul_hi_u32 v1, v5, v1
	v_mul_lo_u32 v3, v1, v2
	v_sub_u32_e32 v3, v5, v3
	v_add_u32_e32 v4, 1, v1
	v_cmp_ge_u32_e32 vcc, v3, v2
	s_nop 1
	v_cndmask_b32_e32 v1, v1, v4, vcc
	v_sub_u32_e32 v4, v3, v2
	v_cndmask_b32_e32 v3, v3, v4, vcc
	v_add_u32_e32 v4, 1, v1
	v_cmp_ge_u32_e32 vcc, v3, v2
	v_add_u32_e32 v3, 1, v5
	s_nop 0
	v_cndmask_b32_e32 v1, v1, v4, vcc
	v_mul_lo_u32 v4, v2, v1
	v_add_u32_e32 v2, v4, v2
	v_cmp_ne_u32_e32 vcc, v3, v2
	s_and_saveexec_b64 s[2:3], vcc
	s_xor_b64 s[10:11], exec, s[2:3]
	s_cbranch_execz .LBB0_3741
	s_waitcnt lgkmcnt(0)
	s_cmp_lt_i32 s92, 64
	s_cbranch_scc1 .LBB0_3741
	s_nop 0
	s_nop 0
	s_nop 0
	s_nop 0
	s_nop 0
	s_nop 0
	s_nop 0
	s_nop 0
	s_nop 0
	s_nop 0
	s_nop 0
	s_nop 0
	s_nop 0
	s_nop 0
	v_mov_b32_e32 v0, 0x3500
	global_load_dword v0, v0, s[74:75] sc1
	s_add_u32 s18, s74, 0x3500
	s_addc_u32 s19, s75, 0
	s_waitcnt vmcnt(0)
	v_cmp_eq_u32_e32 vcc, v0, v1
	s_and_saveexec_b64 s[12:13], vcc
	s_cbranch_execz .LBB0_3740
	s_mov_b32 s2, 1
	s_mov_b64 s[30:31], 0
	v_mov_b32_e32 v0, 0
	s_branch .LBB0_3731

; __device__ __forceinline__ unsigned xb_ld(unsigned* p)              { return __hip_atomic_load(p, __ATOMIC_RELAXED, __HIP_MEMORY_SCOPE_AGENT); }
; __device__ __forceinline__ unsigned xb_add(unsigned* p, unsigned v) { return __hip_atomic_fetch_add(p, v, __ATOMIC_RELAXED, __HIP_MEMORY_SCOPE_AGENT); }
; #define XB_SPIN(cond, bar) do { unsigned _sp = 0; while (cond) { __builtin_amdgcn_s_sleep(1); \
;     if ((++_sp & 255u) == 0u) { if (xb_ld(&(bar)[XB_TMO])) break; if (_sp > XB_SPIN_CAP) { atomicAdd(&(bar)[XB_TMO], 1u); break; } } } } while (0)
; __device__ __forceinline__ void xcd_barrier(const XcdBarrier& b) {
;     ...
;         const unsigned old = xb_add(&bar[XB_XSUB(b.x)], 1u);
;         const unsigned gen = old / nloc;
;         if (old + 1u == (gen + 1u) * nloc) {
;             __builtin_amdgcn_fence(__ATOMIC_RELEASE, "agent");
;             asm volatile("s_waitcnt vmcnt(0)" ::: "memory");
;             const unsigned og = xb_add(&bar[XB_TOP], 1u);
;             const unsigned tg = og / nx;
;             if (og + 1u == (tg + 1u) * nx) xb_add(&bar[XB_TOPGEN], 1u);
;             else XB_SPIN(xb_ld(&bar[XB_TOPGEN]) == tg, bar);
;             __builtin_amdgcn_fence(__ATOMIC_ACQUIRE, "agent");
;             xb_add(&bar[XB_XGEN(b.x)], 1u);
;             asm volatile("s_waitcnt vmcnt(0)" ::: "memory");
;         } else {
;             XB_SPIN(xb_ld(&bar[XB_XGEN(b.x)]) == gen, bar);
;             __builtin_amdgcn_fence(__ATOMIC_ACQUIRE, "agent");
;             asm volatile("s_waitcnt vmcnt(0)" ::: "memory");
.LBB0_4140:
	s_or_b64 exec, exec, s[10:11]
	v_cvt_f32_u32_e32 v4, v2
	s_waitcnt vmcnt(0)
	v_readfirstlane_b32 s2, v3
	v_sub_u32_e32 v3, 0, v2
	v_rcp_iflag_f32_e32 v4, v4
	v_add_u32_e32 v5, s2, v1
	v_mul_f32_e32 v4, 0x4f7ffffe, v4
	v_cvt_u32_f32_e32 v4, v4
	v_mul_lo_u32 v1, v3, v4
	v_mul_hi_u32 v1, v4, v1
	v_add_u32_e32 v1, v4, v1
	v_mul_hi_u32 v1, v5, v1
	v_mul_lo_u32 v3, v1, v2
	v_sub_u32_e32 v3, v5, v3
	v_add_u32_e32 v4, 1, v1
	v_cmp_ge_u32_e32 vcc, v3, v2
	s_nop 1
	v_cndmask_b32_e32 v1, v1, v4, vcc
	v_sub_u32_e32 v4, v3, v2
	v_cndmask_b32_e32 v3, v3, v4, vcc
	v_add_u32_e32 v4, 1, v1
	v_cmp_ge_u32_e32 vcc, v3, v2
	v_add_u32_e32 v3, 1, v5
	s_nop 0
	v_cndmask_b32_e32 v1, v1, v4, vcc
	v_mul_lo_u32 v4, v2, v1
	v_add_u32_e32 v2, v4, v2
	v_cmp_ne_u32_e32 vcc, v3, v2
	s_and_saveexec_b64 s[2:3], vcc
	s_xor_b64 s[8:9], exec, s[2:3]
	s_cbranch_execz .LBB0_4154
	s_waitcnt lgkmcnt(0)
	v_mov_b32_e32 v0, 0x3500
	global_load_dword v0, v0, s[74:75] sc1
	s_add_u32 s12, s74, 0x3500
	s_addc_u32 s13, s75, 0
	s_waitcnt vmcnt(0)
	v_cmp_eq_u32_e32 vcc, v0, v1
	s_and_saveexec_b64 s[10:11], vcc
	s_cbranch_execz .LBB0_4153
	s_mov_b32 s2, 1
	s_mov_b64 s[18:19], 0
	v_mov_b32_e32 v0, 0
	s_branch .LBB0_4144

; __device__ __forceinline__ unsigned xb_ld(unsigned* p)              { return __hip_atomic_load(p, __ATOMIC_RELAXED, __HIP_MEMORY_SCOPE_AGENT); }
; __device__ __forceinline__ unsigned xb_add(unsigned* p, unsigned v) { return __hip_atomic_fetch_add(p, v, __ATOMIC_RELAXED, __HIP_MEMORY_SCOPE_AGENT); }
; #define XB_SPIN(cond, bar) do { unsigned _sp = 0; while (cond) { __builtin_amdgcn_s_sleep(1); \
;     if ((++_sp & 255u) == 0u) { if (xb_ld(&(bar)[XB_TMO])) break; if (_sp > XB_SPIN_CAP) { atomicAdd(&(bar)[XB_TMO], 1u); break; } } } } while (0)
; __device__ __forceinline__ void xcd_barrier(const XcdBarrier& b) {
;     ...
;         const unsigned old = xb_add(&bar[XB_XSUB(b.x)], 1u);
;         const unsigned gen = old / nloc;
;         if (old + 1u == (gen + 1u) * nloc) {
;             __builtin_amdgcn_fence(__ATOMIC_RELEASE, "agent");
;             asm volatile("s_waitcnt vmcnt(0)" ::: "memory");
;             const unsigned og = xb_add(&bar[XB_TOP], 1u);
;             const unsigned tg = og / nx;
;             if (og + 1u == (tg + 1u) * nx) xb_add(&bar[XB_TOPGEN], 1u);
;             else XB_SPIN(xb_ld(&bar[XB_TOPGEN]) == tg, bar);
;             __builtin_amdgcn_fence(__ATOMIC_ACQUIRE, "agent");
;             xb_add(&bar[XB_XGEN(b.x)], 1u);
;             asm volatile("s_waitcnt vmcnt(0)" ::: "memory");
;         } else {
;             XB_SPIN(xb_ld(&bar[XB_XGEN(b.x)]) == gen, bar);
;             __builtin_amdgcn_fence(__ATOMIC_ACQUIRE, "agent");
;             asm volatile("s_waitcnt vmcnt(0)" ::: "memory");
.LBB0_4588:
	s_or_b64 exec, exec, s[6:7]
	v_cvt_f32_u32_e32 v4, v2
	s_waitcnt vmcnt(0)
	v_readfirstlane_b32 s4, v3
	v_sub_u32_e32 v3, 0, v2
	v_rcp_iflag_f32_e32 v4, v4
	v_add_u32_e32 v5, s4, v1
	v_mul_f32_e32 v4, 0x4f7ffffe, v4
	v_cvt_u32_f32_e32 v4, v4
	v_mul_lo_u32 v1, v3, v4
	v_mul_hi_u32 v1, v4, v1
	v_add_u32_e32 v1, v4, v1
	v_mul_hi_u32 v1, v5, v1
	v_mul_lo_u32 v3, v1, v2
	v_sub_u32_e32 v3, v5, v3
	v_add_u32_e32 v4, 1, v1
	v_cmp_ge_u32_e32 vcc, v3, v2
	s_nop 1
	v_cndmask_b32_e32 v1, v1, v4, vcc
	v_sub_u32_e32 v4, v3, v2
	v_cndmask_b32_e32 v3, v3, v4, vcc
	v_add_u32_e32 v4, 1, v1
	v_cmp_ge_u32_e32 vcc, v3, v2
	v_add_u32_e32 v3, 1, v5
	s_nop 0
	v_cndmask_b32_e32 v1, v1, v4, vcc
	v_mul_lo_u32 v4, v2, v1
	v_add_u32_e32 v2, v4, v2
	v_cmp_ne_u32_e32 vcc, v3, v2
	s_and_saveexec_b64 s[4:5], vcc
	s_xor_b64 s[4:5], exec, s[4:5]
	s_cbranch_execz .LBB0_4602
	s_waitcnt lgkmcnt(0)
	v_mov_b32_e32 v0, 0x3500
	global_load_dword v0, v0, s[74:75] sc1
	s_add_u32 s8, s74, 0x3500
	s_addc_u32 s9, s75, 0
	s_waitcnt vmcnt(0)
	v_cmp_eq_u32_e32 vcc, v0, v1
	s_and_saveexec_b64 s[6:7], vcc
	s_cbranch_execz .LBB0_4601
	s_mov_b32 s22, 1
	s_mov_b64 s[10:11], 0
	v_mov_b32_e32 v0, 0
	s_branch .LBB0_4592
